# v31: RG-LRU next task's causal-conv staging moved from the loop top (pre-publish critical path) into the post-publish look-back window; first task's conv peeled in front of the loop
# speedup vs baseline: 1.0038x; 1.0021x over previous
.LBB0_331:
	v_fmac_f32_e32 v115, v114, v117
	v_mul_f32_e32 v177, v114, v178
	s_and_saveexec_b64 s[0:1], s[52:53]
	s_cbranch_execz .LBB0_340
	s_add_i32 s68, s73, s33
	s_ashr_i32 s69, s68, 31
	s_lshl_b64 s[68:69], s[68:69], 12
	s_add_u32 s68, s36, s68
	v_or_b32_e32 v114, 1, v177
	s_addc_u32 s69, s37, s69
	global_store_dwordx2 v112, v[114:115], s[68:69] sc1
	s_or_b64 exec, exec, s[0:1]
	s_waitcnt vmcnt(1)
	v_lshlrev_b32_e32 v179, 16, v101
	v_mul_f32_e32 v222, 0x3d372713, v179
	v_mul_f32_e32 v222, v222, v179
	v_fma_f32 v222, v222, v179, v179
	v_mul_f32_e32 v222, 0x3f4c422a, v222
	v_add_f32_e32 v222, v222, v222
	v_mul_f32_e32 v222, 0x3fb8aa3b, v222
	v_exp_f32_e32 v222, v222
	v_mul_f32_e32 v179, 0.5, v179
	v_add_f32_e32 v222, 1.0, v222
	v_rcp_f32_e32 v222, v222
	s_nop 0
	v_fma_f32 v222, v222, -2.0, 1.0
	v_add_f32_e32 v222, 1.0, v222
	v_mul_f32_e32 v188, v179, v222
	v_lshlrev_b32_e32 v179, 16, v162
	v_mul_f32_e32 v222, 0x3d372713, v179
	v_mul_f32_e32 v222, v222, v179
	v_fma_f32 v222, v222, v179, v179
	v_mul_f32_e32 v222, 0x3f4c422a, v222
	v_add_f32_e32 v222, v222, v222
	v_mul_f32_e32 v222, 0x3fb8aa3b, v222
	v_exp_f32_e32 v222, v222
	v_mul_f32_e32 v179, 0.5, v179
	v_add_f32_e32 v222, 1.0, v222
	v_rcp_f32_e32 v222, v222
	s_nop 0
	v_fma_f32 v222, v222, -2.0, 1.0
	v_add_f32_e32 v222, 1.0, v222
	v_mul_f32_e32 v189, v179, v222
	v_lshlrev_b32_e32 v179, 16, v161
	v_mul_f32_e32 v222, 0x3d372713, v179
	v_mul_f32_e32 v222, v222, v179
	v_fma_f32 v222, v222, v179, v179
	v_mul_f32_e32 v222, 0x3f4c422a, v222
	v_add_f32_e32 v222, v222, v222
	v_mul_f32_e32 v222, 0x3fb8aa3b, v222
	v_exp_f32_e32 v222, v222
	v_mul_f32_e32 v179, 0.5, v179
	v_add_f32_e32 v222, 1.0, v222
	v_rcp_f32_e32 v222, v222
	s_nop 0
	v_fma_f32 v222, v222, -2.0, 1.0
	v_add_f32_e32 v222, 1.0, v222
	v_mul_f32_e32 v190, v179, v222
	v_lshlrev_b32_e32 v179, 16, v160
	v_mul_f32_e32 v222, 0x3d372713, v179
	v_mul_f32_e32 v222, v222, v179
	v_fma_f32 v222, v222, v179, v179
	v_mul_f32_e32 v222, 0x3f4c422a, v222
	v_add_f32_e32 v222, v222, v222
	v_mul_f32_e32 v222, 0x3fb8aa3b, v222
	v_exp_f32_e32 v222, v222
	v_mul_f32_e32 v179, 0.5, v179
	v_add_f32_e32 v222, 1.0, v222
	v_rcp_f32_e32 v222, v222
	s_nop 0
	v_fma_f32 v222, v222, -2.0, 1.0
	v_add_f32_e32 v222, 1.0, v222
	v_mul_f32_e32 v191, v179, v222
	v_lshlrev_b32_e32 v179, 16, v159
	v_mul_f32_e32 v222, 0x3d372713, v179
	v_mul_f32_e32 v222, v222, v179
	v_fma_f32 v222, v222, v179, v179
	v_mul_f32_e32 v222, 0x3f4c422a, v222
	v_add_f32_e32 v222, v222, v222
	v_mul_f32_e32 v222, 0x3fb8aa3b, v222
	v_exp_f32_e32 v222, v222
	v_mul_f32_e32 v179, 0.5, v179
	v_add_f32_e32 v222, 1.0, v222
	v_rcp_f32_e32 v222, v222
	s_nop 0
	v_fma_f32 v222, v222, -2.0, 1.0
	v_add_f32_e32 v222, 1.0, v222
	v_mul_f32_e32 v192, v179, v222
	v_lshlrev_b32_e32 v179, 16, v158
	v_mul_f32_e32 v222, 0x3d372713, v179
	v_mul_f32_e32 v222, v222, v179
	v_fma_f32 v222, v222, v179, v179
	v_mul_f32_e32 v222, 0x3f4c422a, v222
	v_add_f32_e32 v222, v222, v222
	v_mul_f32_e32 v222, 0x3fb8aa3b, v222
	v_exp_f32_e32 v222, v222
	v_mul_f32_e32 v179, 0.5, v179
	v_add_f32_e32 v222, 1.0, v222
	v_rcp_f32_e32 v222, v222
	s_nop 0
	v_fma_f32 v222, v222, -2.0, 1.0
	v_add_f32_e32 v222, 1.0, v222
	v_mul_f32_e32 v193, v179, v222
	v_lshlrev_b32_e32 v179, 16, v157
	v_mul_f32_e32 v222, 0x3d372713, v179
	v_mul_f32_e32 v222, v222, v179
	v_fma_f32 v222, v222, v179, v179
	v_mul_f32_e32 v222, 0x3f4c422a, v222
	v_add_f32_e32 v222, v222, v222
	v_mul_f32_e32 v222, 0x3fb8aa3b, v222
	v_exp_f32_e32 v222, v222
	v_mul_f32_e32 v179, 0.5, v179
	v_add_f32_e32 v222, 1.0, v222
	v_rcp_f32_e32 v222, v222
	s_nop 0
	v_fma_f32 v222, v222, -2.0, 1.0
	v_add_f32_e32 v222, 1.0, v222
	v_mul_f32_e32 v194, v179, v222
	v_lshlrev_b32_e32 v179, 16, v156
	v_mul_f32_e32 v222, 0x3d372713, v179
	v_mul_f32_e32 v222, v222, v179
	v_fma_f32 v222, v222, v179, v179
	v_mul_f32_e32 v222, 0x3f4c422a, v222
	v_add_f32_e32 v222, v222, v222
	v_mul_f32_e32 v222, 0x3fb8aa3b, v222
	v_exp_f32_e32 v222, v222
	v_mul_f32_e32 v179, 0.5, v179
	v_add_f32_e32 v222, 1.0, v222
	v_rcp_f32_e32 v222, v222
	s_nop 0
	v_fma_f32 v222, v222, -2.0, 1.0
	v_add_f32_e32 v222, 1.0, v222
	v_mul_f32_e32 v195, v179, v222
	v_lshlrev_b32_e32 v226, 16, v6
	v_and_b32_e32 v227, 0xffff0000, v6
	v_pk_fma_f32 v[226:227], v[26:27], v[226:227], v[30:31]
	v_lshlrev_b32_e32 v228, 16, v2
	v_and_b32_e32 v229, 0xffff0000, v2
	v_pk_fma_f32 v[226:227], v[38:39], v[228:229], v[226:227]
	v_lshlrev_b32_e32 v228, 16, v10
	v_and_b32_e32 v229, 0xffff0000, v10
	v_pk_fma_f32 v[226:227], v[46:47], v[228:229], v[226:227]
	v_lshlrev_b32_e32 v228, 16, v14
	v_and_b32_e32 v229, 0xffff0000, v14
	v_pk_fma_f32 v[226:227], v[54:55], v[228:229], v[226:227]
	v_lshlrev_b32_e32 v228, 16, v7
	v_and_b32_e32 v229, 0xffff0000, v7
	v_pk_fma_f32 v[228:229], v[28:29], v[228:229], v[32:33]
	v_lshlrev_b32_e32 v230, 16, v3
	v_and_b32_e32 v231, 0xffff0000, v3
	v_pk_fma_f32 v[228:229], v[40:41], v[230:231], v[228:229]
	v_lshlrev_b32_e32 v230, 16, v11
	v_and_b32_e32 v231, 0xffff0000, v11
	v_pk_fma_f32 v[228:229], v[48:49], v[230:231], v[228:229]
	v_lshlrev_b32_e32 v230, 16, v15
	v_and_b32_e32 v231, 0xffff0000, v15
	v_pk_fma_f32 v[228:229], v[56:57], v[230:231], v[228:229]
	v_lshlrev_b32_e32 v230, 16, v8
	v_and_b32_e32 v231, 0xffff0000, v8
	v_pk_fma_f32 v[230:231], v[18:19], v[230:231], v[22:23]
	v_lshlrev_b32_e32 v232, 16, v4
	v_and_b32_e32 v233, 0xffff0000, v4
	v_pk_fma_f32 v[230:231], v[34:35], v[232:233], v[230:231]
	v_lshlrev_b32_e32 v232, 16, v12
	v_and_b32_e32 v233, 0xffff0000, v12
	v_pk_fma_f32 v[230:231], v[42:43], v[232:233], v[230:231]
	v_lshlrev_b32_e32 v232, 16, v16
	v_and_b32_e32 v233, 0xffff0000, v16
	v_pk_fma_f32 v[230:231], v[50:51], v[232:233], v[230:231]
	v_lshlrev_b32_e32 v232, 16, v9
	v_and_b32_e32 v233, 0xffff0000, v9
	v_pk_fma_f32 v[232:233], v[20:21], v[232:233], v[24:25]
	v_lshlrev_b32_e32 v234, 16, v5
	v_and_b32_e32 v235, 0xffff0000, v5
	v_pk_fma_f32 v[232:233], v[36:37], v[234:235], v[232:233]
	v_lshlrev_b32_e32 v234, 16, v13
	v_and_b32_e32 v235, 0xffff0000, v13
	v_pk_fma_f32 v[232:233], v[44:45], v[234:235], v[232:233]
	v_lshlrev_b32_e32 v234, 16, v17
	v_and_b32_e32 v235, 0xffff0000, v17
	v_pk_fma_f32 v[232:233], v[52:53], v[234:235], v[232:233]
	v_cvt_pk_bf16_f32 v234, v226, v227
	v_cvt_pk_bf16_f32 v235, v228, v229
	v_cvt_pk_bf16_f32 v236, v230, v231
	v_add_u32_e32 v238, v122, v90
	v_cvt_pk_bf16_f32 v237, v232, v233
	ds_write_b128 v238, v[234:237]
	ds_write_b128 v123, v[226:229] offset:9216
	ds_write_b128 v123, v[230:233] offset:9232
	s_and_saveexec_b64 s[68:69], s[44:45]
	s_cbranch_execnz .LBB0_341

.LBB0_340:
	s_or_b64 exec, exec, s[0:1]
	s_waitcnt vmcnt(0)
	v_lshlrev_b32_e32 v179, 16, v101
	v_mul_f32_e32 v222, 0x3d372713, v179
	v_mul_f32_e32 v222, v222, v179
	v_fma_f32 v222, v222, v179, v179
	v_mul_f32_e32 v222, 0x3f4c422a, v222
	v_add_f32_e32 v222, v222, v222
	v_mul_f32_e32 v222, 0x3fb8aa3b, v222
	v_exp_f32_e32 v222, v222
	v_mul_f32_e32 v179, 0.5, v179
	v_add_f32_e32 v222, 1.0, v222
	v_rcp_f32_e32 v222, v222
	s_nop 0
	v_fma_f32 v222, v222, -2.0, 1.0
	v_add_f32_e32 v222, 1.0, v222
	v_mul_f32_e32 v188, v179, v222
	v_lshlrev_b32_e32 v179, 16, v162
	v_mul_f32_e32 v222, 0x3d372713, v179
	v_mul_f32_e32 v222, v222, v179
	v_fma_f32 v222, v222, v179, v179
	v_mul_f32_e32 v222, 0x3f4c422a, v222
	v_add_f32_e32 v222, v222, v222
	v_mul_f32_e32 v222, 0x3fb8aa3b, v222
	v_exp_f32_e32 v222, v222
	v_mul_f32_e32 v179, 0.5, v179
	v_add_f32_e32 v222, 1.0, v222
	v_rcp_f32_e32 v222, v222
	s_nop 0
	v_fma_f32 v222, v222, -2.0, 1.0
	v_add_f32_e32 v222, 1.0, v222
	v_mul_f32_e32 v189, v179, v222
	v_lshlrev_b32_e32 v179, 16, v161
	v_mul_f32_e32 v222, 0x3d372713, v179
	v_mul_f32_e32 v222, v222, v179
	v_fma_f32 v222, v222, v179, v179
	v_mul_f32_e32 v222, 0x3f4c422a, v222
	v_add_f32_e32 v222, v222, v222
	v_mul_f32_e32 v222, 0x3fb8aa3b, v222
	v_exp_f32_e32 v222, v222
	v_mul_f32_e32 v179, 0.5, v179
	v_add_f32_e32 v222, 1.0, v222
	v_rcp_f32_e32 v222, v222
	s_nop 0
	v_fma_f32 v222, v222, -2.0, 1.0
	v_add_f32_e32 v222, 1.0, v222
	v_mul_f32_e32 v190, v179, v222
	v_lshlrev_b32_e32 v179, 16, v160
	v_mul_f32_e32 v222, 0x3d372713, v179
	v_mul_f32_e32 v222, v222, v179
	v_fma_f32 v222, v222, v179, v179
	v_mul_f32_e32 v222, 0x3f4c422a, v222
	v_add_f32_e32 v222, v222, v222
	v_mul_f32_e32 v222, 0x3fb8aa3b, v222
	v_exp_f32_e32 v222, v222
	v_mul_f32_e32 v179, 0.5, v179
	v_add_f32_e32 v222, 1.0, v222
	v_rcp_f32_e32 v222, v222
	s_nop 0
	v_fma_f32 v222, v222, -2.0, 1.0
	v_add_f32_e32 v222, 1.0, v222
	v_mul_f32_e32 v191, v179, v222
	v_lshlrev_b32_e32 v179, 16, v159
	v_mul_f32_e32 v222, 0x3d372713, v179
	v_mul_f32_e32 v222, v222, v179
	v_fma_f32 v222, v222, v179, v179
	v_mul_f32_e32 v222, 0x3f4c422a, v222
	v_add_f32_e32 v222, v222, v222
	v_mul_f32_e32 v222, 0x3fb8aa3b, v222
	v_exp_f32_e32 v222, v222
	v_mul_f32_e32 v179, 0.5, v179
	v_add_f32_e32 v222, 1.0, v222
	v_rcp_f32_e32 v222, v222
	s_nop 0
	v_fma_f32 v222, v222, -2.0, 1.0
	v_add_f32_e32 v222, 1.0, v222
	v_mul_f32_e32 v192, v179, v222
	v_lshlrev_b32_e32 v179, 16, v158
	v_mul_f32_e32 v222, 0x3d372713, v179
	v_mul_f32_e32 v222, v222, v179
	v_fma_f32 v222, v222, v179, v179
	v_mul_f32_e32 v222, 0x3f4c422a, v222
	v_add_f32_e32 v222, v222, v222
	v_mul_f32_e32 v222, 0x3fb8aa3b, v222
	v_exp_f32_e32 v222, v222
	v_mul_f32_e32 v179, 0.5, v179
	v_add_f32_e32 v222, 1.0, v222
	v_rcp_f32_e32 v222, v222
	s_nop 0
	v_fma_f32 v222, v222, -2.0, 1.0
	v_add_f32_e32 v222, 1.0, v222
	v_mul_f32_e32 v193, v179, v222
	v_lshlrev_b32_e32 v179, 16, v157
	v_mul_f32_e32 v222, 0x3d372713, v179
	v_mul_f32_e32 v222, v222, v179
	v_fma_f32 v222, v222, v179, v179
	v_mul_f32_e32 v222, 0x3f4c422a, v222
	v_add_f32_e32 v222, v222, v222
	v_mul_f32_e32 v222, 0x3fb8aa3b, v222
	v_exp_f32_e32 v222, v222
	v_mul_f32_e32 v179, 0.5, v179
	v_add_f32_e32 v222, 1.0, v222
	v_rcp_f32_e32 v222, v222
	s_nop 0
	v_fma_f32 v222, v222, -2.0, 1.0
	v_add_f32_e32 v222, 1.0, v222
	v_mul_f32_e32 v194, v179, v222
	v_lshlrev_b32_e32 v179, 16, v156
	v_mul_f32_e32 v222, 0x3d372713, v179
	v_mul_f32_e32 v222, v222, v179
	v_fma_f32 v222, v222, v179, v179
	v_mul_f32_e32 v222, 0x3f4c422a, v222
	v_add_f32_e32 v222, v222, v222
	v_mul_f32_e32 v222, 0x3fb8aa3b, v222
	v_exp_f32_e32 v222, v222
	v_mul_f32_e32 v179, 0.5, v179
	v_add_f32_e32 v222, 1.0, v222
	v_rcp_f32_e32 v222, v222
	s_nop 0
	v_fma_f32 v222, v222, -2.0, 1.0
	v_add_f32_e32 v222, 1.0, v222
	v_mul_f32_e32 v195, v179, v222
	v_lshlrev_b32_e32 v226, 16, v6
	v_and_b32_e32 v227, 0xffff0000, v6
	v_pk_fma_f32 v[226:227], v[26:27], v[226:227], v[30:31]
	v_lshlrev_b32_e32 v228, 16, v2
	v_and_b32_e32 v229, 0xffff0000, v2
	v_pk_fma_f32 v[226:227], v[38:39], v[228:229], v[226:227]
	v_lshlrev_b32_e32 v228, 16, v10
	v_and_b32_e32 v229, 0xffff0000, v10
	v_pk_fma_f32 v[226:227], v[46:47], v[228:229], v[226:227]
	v_lshlrev_b32_e32 v228, 16, v14
	v_and_b32_e32 v229, 0xffff0000, v14
	v_pk_fma_f32 v[226:227], v[54:55], v[228:229], v[226:227]
	v_lshlrev_b32_e32 v228, 16, v7
	v_and_b32_e32 v229, 0xffff0000, v7
	v_pk_fma_f32 v[228:229], v[28:29], v[228:229], v[32:33]
	v_lshlrev_b32_e32 v230, 16, v3
	v_and_b32_e32 v231, 0xffff0000, v3
	v_pk_fma_f32 v[228:229], v[40:41], v[230:231], v[228:229]
	v_lshlrev_b32_e32 v230, 16, v11
	v_and_b32_e32 v231, 0xffff0000, v11
	v_pk_fma_f32 v[228:229], v[48:49], v[230:231], v[228:229]
	v_lshlrev_b32_e32 v230, 16, v15
	v_and_b32_e32 v231, 0xffff0000, v15
	v_pk_fma_f32 v[228:229], v[56:57], v[230:231], v[228:229]
	v_lshlrev_b32_e32 v230, 16, v8
	v_and_b32_e32 v231, 0xffff0000, v8
	v_pk_fma_f32 v[230:231], v[18:19], v[230:231], v[22:23]
	v_lshlrev_b32_e32 v232, 16, v4
	v_and_b32_e32 v233, 0xffff0000, v4
	v_pk_fma_f32 v[230:231], v[34:35], v[232:233], v[230:231]
	v_lshlrev_b32_e32 v232, 16, v12
	v_and_b32_e32 v233, 0xffff0000, v12
	v_pk_fma_f32 v[230:231], v[42:43], v[232:233], v[230:231]
	v_lshlrev_b32_e32 v232, 16, v16
	v_and_b32_e32 v233, 0xffff0000, v16
	v_pk_fma_f32 v[230:231], v[50:51], v[232:233], v[230:231]
	v_lshlrev_b32_e32 v232, 16, v9
	v_and_b32_e32 v233, 0xffff0000, v9
	v_pk_fma_f32 v[232:233], v[20:21], v[232:233], v[24:25]
	v_lshlrev_b32_e32 v234, 16, v5
	v_and_b32_e32 v235, 0xffff0000, v5
	v_pk_fma_f32 v[232:233], v[36:37], v[234:235], v[232:233]
	v_lshlrev_b32_e32 v234, 16, v13
	v_and_b32_e32 v235, 0xffff0000, v13
	v_pk_fma_f32 v[232:233], v[44:45], v[234:235], v[232:233]
	v_lshlrev_b32_e32 v234, 16, v17
	v_and_b32_e32 v235, 0xffff0000, v17
	v_pk_fma_f32 v[232:233], v[52:53], v[234:235], v[232:233]
	v_cvt_pk_bf16_f32 v234, v226, v227
	v_cvt_pk_bf16_f32 v235, v228, v229
	v_cvt_pk_bf16_f32 v236, v230, v231
	v_add_u32_e32 v238, v122, v90
	v_cvt_pk_bf16_f32 v237, v232, v233
	ds_write_b128 v238, v[234:237]
	ds_write_b128 v123, v[226:229] offset:9216
	ds_write_b128 v123, v[230:233] offset:9232
	s_and_saveexec_b64 s[68:69], s[44:45]
	s_cbranch_execz .LBB0_333
